# OUT epilogue row-sum-of-squares butterflies: 128 ds_bpermute replaced by DPP moves (quad_perm / row_half_mirror / row_mirror), bitwise-identical sums
# baseline (speedup 1.0000x reference)
.LBB0_1008:
	v_mul_f32_e32 v127, v127, v127
	v_cmp_lt_i32_e32 vcc, v216, v210
	v_fmac_f32_e32 v127, v126, v126
	v_fmac_f32_e32 v127, v128, v128
	v_cndmask_b32_e32 v154, v209, v216, vcc
	v_lshlrev_b32_e32 v169, 2, v154
	v_fmac_f32_e32 v127, v129, v129
	s_nop 1
	v_mov_b32_dpp v126, v127 quad_perm:[1,0,3,2] row_mask:0xf bank_mask:0xf
	v_cmp_lt_i32_e32 vcc, v215, v210
	v_ashrrev_i32_e32 v167, 31, v166
	s_waitcnt lgkmcnt(0)
	v_add_f32_e32 v126, v127, v126
	v_cndmask_b32_e32 v128, v209, v215, vcc
	v_lshlrev_b32_e32 v172, 2, v128
	s_nop 1
	v_mov_b32_dpp v127, v126 quad_perm:[2,3,0,1] row_mask:0xf bank_mask:0xf
	v_cmp_lt_i32_e32 vcc, v214, v210
	s_waitcnt lgkmcnt(0)
	v_add_f32_e32 v126, v126, v127
	v_cndmask_b32_e32 v128, v209, v214, vcc
	v_lshlrev_b32_e32 v173, 2, v128
	s_nop 1
	v_mov_b32_dpp v127, v126 row_half_mirror row_mask:0xf bank_mask:0xf
	v_cmp_lt_i32_e32 vcc, v213, v210
	s_nop 1
	v_cndmask_b32_e32 v128, v209, v213, vcc
	v_lshlrev_b32_e32 v174, 2, v128
	s_waitcnt lgkmcnt(0)
	v_add_f32_e32 v128, v126, v127
	s_nop 1
	v_mov_b32_dpp v129, v128 row_mirror row_mask:0xf bank_mask:0xf
	v_lshl_add_u64 v[126:127], v[166:167], 2, v[190:191]
	s_and_saveexec_b64 s[2:3], s[38:39]
	s_cbranch_execz .LBB0_1010
	s_waitcnt lgkmcnt(0)
	v_add_f32_e32 v128, v128, v129
	global_atomic_add_f32 v[126:127], v128, off

.LBB0_1014:
	v_mul_f32_e32 v123, v123, v123
	v_fmac_f32_e32 v123, v122, v122
	v_fmac_f32_e32 v123, v124, v124
	v_fmac_f32_e32 v123, v125, v125
	s_nop 1
	v_mov_b32_dpp v122, v123 quad_perm:[1,0,3,2] row_mask:0xf bank_mask:0xf
	s_waitcnt lgkmcnt(0)
	v_add_f32_e32 v122, v123, v122
	s_nop 1
	v_mov_b32_dpp v123, v122 quad_perm:[2,3,0,1] row_mask:0xf bank_mask:0xf
	s_waitcnt lgkmcnt(0)
	v_add_f32_e32 v122, v122, v123
	s_nop 1
	v_mov_b32_dpp v123, v122 row_half_mirror row_mask:0xf bank_mask:0xf
	s_waitcnt lgkmcnt(0)
	v_add_f32_e32 v122, v122, v123
	s_nop 1
	v_mov_b32_dpp v123, v122 row_mirror row_mask:0xf bank_mask:0xf
	s_and_saveexec_b64 s[2:3], s[38:39]
	s_cbranch_execz .LBB0_1016
	s_waitcnt lgkmcnt(0)
	v_add_f32_e32 v122, v122, v123
	global_atomic_add_f32 v[126:127], v122, off offset:16

.LBB0_1020:
	v_mul_f32_e32 v119, v119, v119
	v_fmac_f32_e32 v119, v118, v118
	v_fmac_f32_e32 v119, v120, v120
	v_fmac_f32_e32 v119, v121, v121
	s_nop 1
	v_mov_b32_dpp v118, v119 quad_perm:[1,0,3,2] row_mask:0xf bank_mask:0xf
	s_waitcnt lgkmcnt(0)
	v_add_f32_e32 v118, v119, v118
	s_nop 1
	v_mov_b32_dpp v119, v118 quad_perm:[2,3,0,1] row_mask:0xf bank_mask:0xf
	s_waitcnt lgkmcnt(0)
	v_add_f32_e32 v118, v118, v119
	s_nop 1
	v_mov_b32_dpp v119, v118 row_half_mirror row_mask:0xf bank_mask:0xf
	s_waitcnt lgkmcnt(0)
	v_add_f32_e32 v118, v118, v119
	s_nop 1
	v_mov_b32_dpp v119, v118 row_mirror row_mask:0xf bank_mask:0xf
	s_and_saveexec_b64 s[2:3], s[38:39]
	s_cbranch_execz .LBB0_1022
	s_waitcnt lgkmcnt(0)
	v_add_f32_e32 v118, v118, v119
	global_atomic_add_f32 v[126:127], v118, off offset:32

.LBB0_1026:
	v_mul_f32_e32 v115, v115, v115
	v_fmac_f32_e32 v115, v114, v114
	v_fmac_f32_e32 v115, v116, v116
	v_fmac_f32_e32 v115, v117, v117
	s_nop 1
	v_mov_b32_dpp v114, v115 quad_perm:[1,0,3,2] row_mask:0xf bank_mask:0xf
	s_waitcnt lgkmcnt(0)
	v_add_f32_e32 v114, v115, v114
	s_nop 1
	v_mov_b32_dpp v115, v114 quad_perm:[2,3,0,1] row_mask:0xf bank_mask:0xf
	s_waitcnt lgkmcnt(0)
	v_add_f32_e32 v114, v114, v115
	s_nop 1
	v_mov_b32_dpp v115, v114 row_half_mirror row_mask:0xf bank_mask:0xf
	s_waitcnt lgkmcnt(0)
	v_add_f32_e32 v114, v114, v115
	s_nop 1
	v_mov_b32_dpp v115, v114 row_mirror row_mask:0xf bank_mask:0xf
	s_and_saveexec_b64 s[2:3], s[38:39]
	s_cbranch_execz .LBB0_1028
	s_waitcnt lgkmcnt(0)
	v_add_f32_e32 v114, v114, v115
	global_atomic_add_f32 v[126:127], v114, off offset:48

.LBB0_1032:
	v_mul_f32_e32 v111, v111, v111
	v_fmac_f32_e32 v111, v110, v110
	v_fmac_f32_e32 v111, v112, v112
	v_fmac_f32_e32 v111, v113, v113
	s_nop 1
	v_mov_b32_dpp v110, v111 quad_perm:[1,0,3,2] row_mask:0xf bank_mask:0xf
	s_waitcnt lgkmcnt(0)
	v_add_f32_e32 v110, v111, v110
	s_nop 1
	v_mov_b32_dpp v111, v110 quad_perm:[2,3,0,1] row_mask:0xf bank_mask:0xf
	s_waitcnt lgkmcnt(0)
	v_add_f32_e32 v110, v110, v111
	s_nop 1
	v_mov_b32_dpp v111, v110 row_half_mirror row_mask:0xf bank_mask:0xf
	s_waitcnt lgkmcnt(0)
	v_add_f32_e32 v110, v110, v111
	s_nop 1
	v_mov_b32_dpp v111, v110 row_mirror row_mask:0xf bank_mask:0xf
	s_and_saveexec_b64 s[2:3], s[38:39]
	s_cbranch_execz .LBB0_1034
	s_waitcnt lgkmcnt(0)
	v_add_f32_e32 v110, v110, v111
	global_atomic_add_f32 v[126:127], v110, off offset:64

.LBB0_1038:
	v_mul_f32_e32 v107, v107, v107
	v_fmac_f32_e32 v107, v106, v106
	v_fmac_f32_e32 v107, v108, v108
	v_fmac_f32_e32 v107, v109, v109
	s_nop 1
	v_mov_b32_dpp v106, v107 quad_perm:[1,0,3,2] row_mask:0xf bank_mask:0xf
	s_waitcnt lgkmcnt(0)
	v_add_f32_e32 v106, v107, v106
	s_nop 1
	v_mov_b32_dpp v107, v106 quad_perm:[2,3,0,1] row_mask:0xf bank_mask:0xf
	s_waitcnt lgkmcnt(0)
	v_add_f32_e32 v106, v106, v107
	s_nop 1
	v_mov_b32_dpp v107, v106 row_half_mirror row_mask:0xf bank_mask:0xf
	s_waitcnt lgkmcnt(0)
	v_add_f32_e32 v106, v106, v107
	s_nop 1
	v_mov_b32_dpp v107, v106 row_mirror row_mask:0xf bank_mask:0xf
	s_and_saveexec_b64 s[2:3], s[38:39]
	s_cbranch_execz .LBB0_1040
	s_waitcnt lgkmcnt(0)
	v_add_f32_e32 v106, v106, v107
	global_atomic_add_f32 v[126:127], v106, off offset:80

.LBB0_1044:
	v_mul_f32_e32 v103, v103, v103
	v_fmac_f32_e32 v103, v102, v102
	v_fmac_f32_e32 v103, v104, v104
	v_fmac_f32_e32 v103, v105, v105
	s_nop 1
	v_mov_b32_dpp v102, v103 quad_perm:[1,0,3,2] row_mask:0xf bank_mask:0xf
	s_waitcnt lgkmcnt(0)
	v_add_f32_e32 v102, v103, v102
	s_nop 1
	v_mov_b32_dpp v103, v102 quad_perm:[2,3,0,1] row_mask:0xf bank_mask:0xf
	s_waitcnt lgkmcnt(0)
	v_add_f32_e32 v102, v102, v103
	s_nop 1
	v_mov_b32_dpp v103, v102 row_half_mirror row_mask:0xf bank_mask:0xf
	s_waitcnt lgkmcnt(0)
	v_add_f32_e32 v102, v102, v103
	s_nop 1
	v_mov_b32_dpp v103, v102 row_mirror row_mask:0xf bank_mask:0xf
	s_and_saveexec_b64 s[2:3], s[38:39]
	s_cbranch_execz .LBB0_1046
	s_waitcnt lgkmcnt(0)
	v_add_f32_e32 v102, v102, v103
	global_atomic_add_f32 v[126:127], v102, off offset:96

.LBB0_1050:
	v_mul_f32_e32 v99, v99, v99
	v_fmac_f32_e32 v99, v98, v98
	v_fmac_f32_e32 v99, v100, v100
	v_fmac_f32_e32 v99, v101, v101
	s_nop 1
	v_mov_b32_dpp v98, v99 quad_perm:[1,0,3,2] row_mask:0xf bank_mask:0xf
	s_waitcnt lgkmcnt(0)
	v_add_f32_e32 v98, v99, v98
	s_nop 1
	v_mov_b32_dpp v99, v98 quad_perm:[2,3,0,1] row_mask:0xf bank_mask:0xf
	s_waitcnt lgkmcnt(0)
	v_add_f32_e32 v98, v98, v99
	s_nop 1
	v_mov_b32_dpp v99, v98 row_half_mirror row_mask:0xf bank_mask:0xf
	s_waitcnt lgkmcnt(0)
	v_add_f32_e32 v98, v98, v99
	s_nop 1
	v_mov_b32_dpp v99, v98 row_mirror row_mask:0xf bank_mask:0xf
	s_and_saveexec_b64 s[2:3], s[38:39]
	s_cbranch_execz .LBB0_1052
	s_waitcnt lgkmcnt(0)
	v_add_f32_e32 v98, v98, v99
	global_atomic_add_f32 v[126:127], v98, off offset:112

.LBB0_1056:
	v_mul_f32_e32 v95, v95, v95
	v_fmac_f32_e32 v95, v94, v94
	v_fmac_f32_e32 v95, v96, v96
	v_fmac_f32_e32 v95, v97, v97
	s_nop 1
	v_mov_b32_dpp v94, v95 quad_perm:[1,0,3,2] row_mask:0xf bank_mask:0xf
	s_waitcnt lgkmcnt(0)
	v_add_f32_e32 v94, v95, v94
	s_nop 1
	v_mov_b32_dpp v95, v94 quad_perm:[2,3,0,1] row_mask:0xf bank_mask:0xf
	s_waitcnt lgkmcnt(0)
	v_add_f32_e32 v94, v94, v95
	s_nop 1
	v_mov_b32_dpp v95, v94 row_half_mirror row_mask:0xf bank_mask:0xf
	s_waitcnt lgkmcnt(0)
	v_add_f32_e32 v94, v94, v95
	s_nop 1
	v_mov_b32_dpp v95, v94 row_mirror row_mask:0xf bank_mask:0xf
	s_and_saveexec_b64 s[2:3], s[38:39]
	s_cbranch_execz .LBB0_1058
	s_waitcnt lgkmcnt(0)
	v_add_f32_e32 v94, v94, v95
	global_atomic_add_f32 v[126:127], v94, off offset:128

.LBB0_1062:
	v_mul_f32_e32 v91, v91, v91
	v_fmac_f32_e32 v91, v90, v90
	v_fmac_f32_e32 v91, v92, v92
	v_fmac_f32_e32 v91, v93, v93
	s_nop 1
	v_mov_b32_dpp v90, v91 quad_perm:[1,0,3,2] row_mask:0xf bank_mask:0xf
	s_waitcnt lgkmcnt(0)
	v_add_f32_e32 v90, v91, v90
	s_nop 1
	v_mov_b32_dpp v91, v90 quad_perm:[2,3,0,1] row_mask:0xf bank_mask:0xf
	s_waitcnt lgkmcnt(0)
	v_add_f32_e32 v90, v90, v91
	s_nop 1
	v_mov_b32_dpp v91, v90 row_half_mirror row_mask:0xf bank_mask:0xf
	s_waitcnt lgkmcnt(0)
	v_add_f32_e32 v90, v90, v91
	s_nop 1
	v_mov_b32_dpp v91, v90 row_mirror row_mask:0xf bank_mask:0xf
	s_and_saveexec_b64 s[2:3], s[38:39]
	s_cbranch_execz .LBB0_1064
	s_waitcnt lgkmcnt(0)
	v_add_f32_e32 v90, v90, v91
	global_atomic_add_f32 v[126:127], v90, off offset:144

.LBB0_1068:
	v_mul_f32_e32 v87, v87, v87
	v_fmac_f32_e32 v87, v86, v86
	v_fmac_f32_e32 v87, v88, v88
	v_fmac_f32_e32 v87, v89, v89
	s_nop 1
	v_mov_b32_dpp v86, v87 quad_perm:[1,0,3,2] row_mask:0xf bank_mask:0xf
	s_waitcnt lgkmcnt(0)
	v_add_f32_e32 v86, v87, v86
	s_nop 1
	v_mov_b32_dpp v87, v86 quad_perm:[2,3,0,1] row_mask:0xf bank_mask:0xf
	s_waitcnt lgkmcnt(0)
	v_add_f32_e32 v86, v86, v87
	s_nop 1
	v_mov_b32_dpp v87, v86 row_half_mirror row_mask:0xf bank_mask:0xf
	s_waitcnt lgkmcnt(0)
	v_add_f32_e32 v86, v86, v87
	s_nop 1
	v_mov_b32_dpp v87, v86 row_mirror row_mask:0xf bank_mask:0xf
	s_and_saveexec_b64 s[2:3], s[38:39]
	s_cbranch_execz .LBB0_1070
	s_waitcnt lgkmcnt(0)
	v_add_f32_e32 v86, v86, v87
	global_atomic_add_f32 v[126:127], v86, off offset:160

.LBB0_1074:
	v_mul_f32_e32 v83, v83, v83
	v_fmac_f32_e32 v83, v82, v82
	v_fmac_f32_e32 v83, v84, v84
	v_fmac_f32_e32 v83, v85, v85
	s_nop 1
	v_mov_b32_dpp v82, v83 quad_perm:[1,0,3,2] row_mask:0xf bank_mask:0xf
	s_waitcnt lgkmcnt(0)
	v_add_f32_e32 v82, v83, v82
	s_nop 1
	v_mov_b32_dpp v83, v82 quad_perm:[2,3,0,1] row_mask:0xf bank_mask:0xf
	s_waitcnt lgkmcnt(0)
	v_add_f32_e32 v82, v82, v83
	s_nop 1
	v_mov_b32_dpp v83, v82 row_half_mirror row_mask:0xf bank_mask:0xf
	s_waitcnt lgkmcnt(0)
	v_add_f32_e32 v82, v82, v83
	s_nop 1
	v_mov_b32_dpp v83, v82 row_mirror row_mask:0xf bank_mask:0xf
	s_and_saveexec_b64 s[2:3], s[38:39]
	s_cbranch_execz .LBB0_1076
	s_waitcnt lgkmcnt(0)
	v_add_f32_e32 v82, v82, v83
	global_atomic_add_f32 v[126:127], v82, off offset:176

.LBB0_1080:
	v_mul_f32_e32 v79, v79, v79
	v_fmac_f32_e32 v79, v78, v78
	v_fmac_f32_e32 v79, v80, v80
	v_fmac_f32_e32 v79, v81, v81
	s_nop 1
	v_mov_b32_dpp v78, v79 quad_perm:[1,0,3,2] row_mask:0xf bank_mask:0xf
	s_waitcnt lgkmcnt(0)
	v_add_f32_e32 v78, v79, v78
	s_nop 1
	v_mov_b32_dpp v79, v78 quad_perm:[2,3,0,1] row_mask:0xf bank_mask:0xf
	s_waitcnt lgkmcnt(0)
	v_add_f32_e32 v78, v78, v79
	s_nop 1
	v_mov_b32_dpp v79, v78 row_half_mirror row_mask:0xf bank_mask:0xf
	s_waitcnt lgkmcnt(0)
	v_add_f32_e32 v78, v78, v79
	s_nop 1
	v_mov_b32_dpp v79, v78 row_mirror row_mask:0xf bank_mask:0xf
	s_and_saveexec_b64 s[2:3], s[38:39]
	s_cbranch_execz .LBB0_1082
	s_waitcnt lgkmcnt(0)
	v_add_f32_e32 v78, v78, v79
	global_atomic_add_f32 v[126:127], v78, off offset:192

.LBB0_1086:
	v_mul_f32_e32 v75, v75, v75
	v_fmac_f32_e32 v75, v74, v74
	v_fmac_f32_e32 v75, v76, v76
	v_fmac_f32_e32 v75, v77, v77
	s_nop 1
	v_mov_b32_dpp v74, v75 quad_perm:[1,0,3,2] row_mask:0xf bank_mask:0xf
	s_waitcnt lgkmcnt(0)
	v_add_f32_e32 v74, v75, v74
	s_nop 1
	v_mov_b32_dpp v75, v74 quad_perm:[2,3,0,1] row_mask:0xf bank_mask:0xf
	s_waitcnt lgkmcnt(0)
	v_add_f32_e32 v74, v74, v75
	s_nop 1
	v_mov_b32_dpp v75, v74 row_half_mirror row_mask:0xf bank_mask:0xf
	s_waitcnt lgkmcnt(0)
	v_add_f32_e32 v74, v74, v75
	s_nop 1
	v_mov_b32_dpp v75, v74 row_mirror row_mask:0xf bank_mask:0xf
	s_and_saveexec_b64 s[2:3], s[38:39]
	s_cbranch_execz .LBB0_1088
	s_waitcnt lgkmcnt(0)
	v_add_f32_e32 v74, v74, v75
	global_atomic_add_f32 v[126:127], v74, off offset:208

.LBB0_1092:
	v_mul_f32_e32 v71, v71, v71
	v_fmac_f32_e32 v71, v70, v70
	v_fmac_f32_e32 v71, v72, v72
	v_fmac_f32_e32 v71, v73, v73
	s_nop 1
	v_mov_b32_dpp v70, v71 quad_perm:[1,0,3,2] row_mask:0xf bank_mask:0xf
	s_waitcnt lgkmcnt(0)
	v_add_f32_e32 v70, v71, v70
	s_nop 1
	v_mov_b32_dpp v71, v70 quad_perm:[2,3,0,1] row_mask:0xf bank_mask:0xf
	s_waitcnt lgkmcnt(0)
	v_add_f32_e32 v70, v70, v71
	s_nop 1
	v_mov_b32_dpp v71, v70 row_half_mirror row_mask:0xf bank_mask:0xf
	s_waitcnt lgkmcnt(0)
	v_add_f32_e32 v70, v70, v71
	s_nop 1
	v_mov_b32_dpp v71, v70 row_mirror row_mask:0xf bank_mask:0xf
	s_and_saveexec_b64 s[2:3], s[38:39]
	s_cbranch_execz .LBB0_1094
	s_waitcnt lgkmcnt(0)
	v_add_f32_e32 v70, v70, v71
	global_atomic_add_f32 v[126:127], v70, off offset:224

.LBB0_1098:
	v_mul_f32_e32 v67, v67, v67
	v_fmac_f32_e32 v67, v66, v66
	v_fmac_f32_e32 v67, v68, v68
	v_fmac_f32_e32 v67, v69, v69
	s_nop 1
	v_mov_b32_dpp v66, v67 quad_perm:[1,0,3,2] row_mask:0xf bank_mask:0xf
	s_waitcnt lgkmcnt(0)
	v_add_f32_e32 v66, v67, v66
	s_nop 1
	v_mov_b32_dpp v67, v66 quad_perm:[2,3,0,1] row_mask:0xf bank_mask:0xf
	s_waitcnt lgkmcnt(0)
	v_add_f32_e32 v66, v66, v67
	s_nop 1
	v_mov_b32_dpp v67, v66 row_half_mirror row_mask:0xf bank_mask:0xf
	s_waitcnt lgkmcnt(0)
	v_add_f32_e32 v66, v66, v67
	s_nop 1
	v_mov_b32_dpp v67, v66 row_mirror row_mask:0xf bank_mask:0xf
	s_and_saveexec_b64 s[2:3], s[38:39]
	s_cbranch_execz .LBB0_1100
	s_waitcnt lgkmcnt(0)
	v_add_f32_e32 v66, v66, v67
	global_atomic_add_f32 v[126:127], v66, off offset:240

.LBB0_1104:
	v_mul_f32_e32 v0, v63, v63
	v_fmac_f32_e32 v0, v62, v62
	v_fmac_f32_e32 v0, v64, v64
	v_fmac_f32_e32 v0, v65, v65
	s_nop 1
	v_mov_b32_dpp v62, v0 quad_perm:[1,0,3,2] row_mask:0xf bank_mask:0xf
	s_waitcnt lgkmcnt(0)
	v_add_f32_e32 v0, v0, v62
	s_nop 1
	v_mov_b32_dpp v62, v0 quad_perm:[2,3,0,1] row_mask:0xf bank_mask:0xf
	s_waitcnt lgkmcnt(0)
	v_add_f32_e32 v0, v0, v62
	s_nop 1
	v_mov_b32_dpp v62, v0 row_half_mirror row_mask:0xf bank_mask:0xf
	s_waitcnt lgkmcnt(0)
	v_add_f32_e32 v0, v0, v62
	s_nop 1
	v_mov_b32_dpp v62, v0 row_mirror row_mask:0xf bank_mask:0xf
	s_and_saveexec_b64 s[2:3], s[38:39]
	s_cbranch_execz .LBB0_1106
	s_waitcnt lgkmcnt(0)
	v_add_f32_e32 v0, v0, v62
	global_atomic_add_f32 v[126:127], v0, off

.LBB0_1110:
	v_mul_f32_e32 v0, v59, v59
	v_fmac_f32_e32 v0, v58, v58
	v_fmac_f32_e32 v0, v60, v60
	v_fmac_f32_e32 v0, v61, v61
	s_nop 1
	v_mov_b32_dpp v58, v0 quad_perm:[1,0,3,2] row_mask:0xf bank_mask:0xf
	s_waitcnt lgkmcnt(0)
	v_add_f32_e32 v0, v0, v58
	s_nop 1
	v_mov_b32_dpp v58, v0 quad_perm:[2,3,0,1] row_mask:0xf bank_mask:0xf
	s_waitcnt lgkmcnt(0)
	v_add_f32_e32 v0, v0, v58
	s_nop 1
	v_mov_b32_dpp v58, v0 row_half_mirror row_mask:0xf bank_mask:0xf
	s_waitcnt lgkmcnt(0)
	v_add_f32_e32 v0, v0, v58
	s_nop 1
	v_mov_b32_dpp v58, v0 row_mirror row_mask:0xf bank_mask:0xf
	s_and_saveexec_b64 s[2:3], s[38:39]
	s_cbranch_execz .LBB0_1112
	s_waitcnt lgkmcnt(0)
	v_add_f32_e32 v0, v0, v58
	global_atomic_add_f32 v[126:127], v0, off offset:16

.LBB0_1116:
	v_mul_f32_e32 v0, v55, v55
	v_fmac_f32_e32 v0, v54, v54
	v_fmac_f32_e32 v0, v56, v56
	v_fmac_f32_e32 v0, v57, v57
	s_nop 1
	v_mov_b32_dpp v54, v0 quad_perm:[1,0,3,2] row_mask:0xf bank_mask:0xf
	s_waitcnt lgkmcnt(0)
	v_add_f32_e32 v0, v0, v54
	s_nop 1
	v_mov_b32_dpp v54, v0 quad_perm:[2,3,0,1] row_mask:0xf bank_mask:0xf
	s_waitcnt lgkmcnt(0)
	v_add_f32_e32 v0, v0, v54
	s_nop 1
	v_mov_b32_dpp v54, v0 row_half_mirror row_mask:0xf bank_mask:0xf
	s_waitcnt lgkmcnt(0)
	v_add_f32_e32 v0, v0, v54
	s_nop 1
	v_mov_b32_dpp v54, v0 row_mirror row_mask:0xf bank_mask:0xf
	s_and_saveexec_b64 s[2:3], s[38:39]
	s_cbranch_execz .LBB0_1118
	s_waitcnt lgkmcnt(0)
	v_add_f32_e32 v0, v0, v54
	global_atomic_add_f32 v[126:127], v0, off offset:32

.LBB0_1122:
	v_mul_f32_e32 v0, v51, v51
	v_fmac_f32_e32 v0, v50, v50
	v_fmac_f32_e32 v0, v52, v52
	v_fmac_f32_e32 v0, v53, v53
	s_nop 1
	v_mov_b32_dpp v50, v0 quad_perm:[1,0,3,2] row_mask:0xf bank_mask:0xf
	s_waitcnt lgkmcnt(0)
	v_add_f32_e32 v0, v0, v50
	s_nop 1
	v_mov_b32_dpp v50, v0 quad_perm:[2,3,0,1] row_mask:0xf bank_mask:0xf
	s_waitcnt lgkmcnt(0)
	v_add_f32_e32 v0, v0, v50
	s_nop 1
	v_mov_b32_dpp v50, v0 row_half_mirror row_mask:0xf bank_mask:0xf
	s_waitcnt lgkmcnt(0)
	v_add_f32_e32 v0, v0, v50
	s_nop 1
	v_mov_b32_dpp v50, v0 row_mirror row_mask:0xf bank_mask:0xf
	s_and_saveexec_b64 s[2:3], s[38:39]
	s_cbranch_execz .LBB0_1124
	s_waitcnt lgkmcnt(0)
	v_add_f32_e32 v0, v0, v50
	global_atomic_add_f32 v[126:127], v0, off offset:48

.LBB0_1128:
	v_mul_f32_e32 v0, v47, v47
	v_fmac_f32_e32 v0, v46, v46
	v_fmac_f32_e32 v0, v48, v48
	v_fmac_f32_e32 v0, v49, v49
	s_nop 1
	v_mov_b32_dpp v46, v0 quad_perm:[1,0,3,2] row_mask:0xf bank_mask:0xf
	s_waitcnt lgkmcnt(0)
	v_add_f32_e32 v0, v0, v46
	s_nop 1
	v_mov_b32_dpp v46, v0 quad_perm:[2,3,0,1] row_mask:0xf bank_mask:0xf
	s_waitcnt lgkmcnt(0)
	v_add_f32_e32 v0, v0, v46
	s_nop 1
	v_mov_b32_dpp v46, v0 row_half_mirror row_mask:0xf bank_mask:0xf
	s_waitcnt lgkmcnt(0)
	v_add_f32_e32 v0, v0, v46
	s_nop 1
	v_mov_b32_dpp v46, v0 row_mirror row_mask:0xf bank_mask:0xf
	s_and_saveexec_b64 s[2:3], s[38:39]
	s_cbranch_execz .LBB0_1130
	s_waitcnt lgkmcnt(0)
	v_add_f32_e32 v0, v0, v46
	global_atomic_add_f32 v[126:127], v0, off offset:64

.LBB0_1134:
	v_mul_f32_e32 v0, v43, v43
	v_fmac_f32_e32 v0, v42, v42
	v_fmac_f32_e32 v0, v44, v44
	v_fmac_f32_e32 v0, v45, v45
	s_nop 1
	v_mov_b32_dpp v42, v0 quad_perm:[1,0,3,2] row_mask:0xf bank_mask:0xf
	s_waitcnt lgkmcnt(0)
	v_add_f32_e32 v0, v0, v42
	s_nop 1
	v_mov_b32_dpp v42, v0 quad_perm:[2,3,0,1] row_mask:0xf bank_mask:0xf
	s_waitcnt lgkmcnt(0)
	v_add_f32_e32 v0, v0, v42
	s_nop 1
	v_mov_b32_dpp v42, v0 row_half_mirror row_mask:0xf bank_mask:0xf
	s_waitcnt lgkmcnt(0)
	v_add_f32_e32 v0, v0, v42
	s_nop 1
	v_mov_b32_dpp v42, v0 row_mirror row_mask:0xf bank_mask:0xf
	s_and_saveexec_b64 s[2:3], s[38:39]
	s_cbranch_execz .LBB0_1136
	s_waitcnt lgkmcnt(0)
	v_add_f32_e32 v0, v0, v42
	global_atomic_add_f32 v[126:127], v0, off offset:80

.LBB0_1140:
	v_mul_f32_e32 v0, v39, v39
	v_fmac_f32_e32 v0, v38, v38
	v_fmac_f32_e32 v0, v40, v40
	v_fmac_f32_e32 v0, v41, v41
	s_nop 1
	v_mov_b32_dpp v38, v0 quad_perm:[1,0,3,2] row_mask:0xf bank_mask:0xf
	s_waitcnt lgkmcnt(0)
	v_add_f32_e32 v0, v0, v38
	s_nop 1
	v_mov_b32_dpp v38, v0 quad_perm:[2,3,0,1] row_mask:0xf bank_mask:0xf
	s_waitcnt lgkmcnt(0)
	v_add_f32_e32 v0, v0, v38
	s_nop 1
	v_mov_b32_dpp v38, v0 row_half_mirror row_mask:0xf bank_mask:0xf
	s_waitcnt lgkmcnt(0)
	v_add_f32_e32 v0, v0, v38
	s_nop 1
	v_mov_b32_dpp v38, v0 row_mirror row_mask:0xf bank_mask:0xf
	s_and_saveexec_b64 s[2:3], s[38:39]
	s_cbranch_execz .LBB0_1142
	s_waitcnt lgkmcnt(0)
	v_add_f32_e32 v0, v0, v38
	global_atomic_add_f32 v[126:127], v0, off offset:96

.LBB0_1146:
	v_mul_f32_e32 v0, v35, v35
	v_fmac_f32_e32 v0, v34, v34
	v_fmac_f32_e32 v0, v36, v36
	v_fmac_f32_e32 v0, v37, v37
	s_nop 1
	v_mov_b32_dpp v34, v0 quad_perm:[1,0,3,2] row_mask:0xf bank_mask:0xf
	s_waitcnt lgkmcnt(0)
	v_add_f32_e32 v0, v0, v34
	s_nop 1
	v_mov_b32_dpp v34, v0 quad_perm:[2,3,0,1] row_mask:0xf bank_mask:0xf
	s_waitcnt lgkmcnt(0)
	v_add_f32_e32 v0, v0, v34
	s_nop 1
	v_mov_b32_dpp v34, v0 row_half_mirror row_mask:0xf bank_mask:0xf
	s_waitcnt lgkmcnt(0)
	v_add_f32_e32 v0, v0, v34
	s_nop 1
	v_mov_b32_dpp v34, v0 row_mirror row_mask:0xf bank_mask:0xf
	s_and_saveexec_b64 s[2:3], s[38:39]
	s_cbranch_execz .LBB0_1148
	s_waitcnt lgkmcnt(0)
	v_add_f32_e32 v0, v0, v34
	global_atomic_add_f32 v[126:127], v0, off offset:112

.LBB0_1152:
	v_mul_f32_e32 v0, v31, v31
	v_fmac_f32_e32 v0, v30, v30
	v_fmac_f32_e32 v0, v32, v32
	v_fmac_f32_e32 v0, v33, v33
	s_nop 1
	v_mov_b32_dpp v30, v0 quad_perm:[1,0,3,2] row_mask:0xf bank_mask:0xf
	s_waitcnt lgkmcnt(0)
	v_add_f32_e32 v0, v0, v30
	s_nop 1
	v_mov_b32_dpp v30, v0 quad_perm:[2,3,0,1] row_mask:0xf bank_mask:0xf
	s_waitcnt lgkmcnt(0)
	v_add_f32_e32 v0, v0, v30
	s_nop 1
	v_mov_b32_dpp v30, v0 row_half_mirror row_mask:0xf bank_mask:0xf
	s_waitcnt lgkmcnt(0)
	v_add_f32_e32 v0, v0, v30
	s_nop 1
	v_mov_b32_dpp v30, v0 row_mirror row_mask:0xf bank_mask:0xf
	s_and_saveexec_b64 s[2:3], s[38:39]
	s_cbranch_execz .LBB0_1154
	s_waitcnt lgkmcnt(0)
	v_add_f32_e32 v0, v0, v30
	global_atomic_add_f32 v[126:127], v0, off offset:128

.LBB0_1158:
	v_mul_f32_e32 v0, v27, v27
	v_fmac_f32_e32 v0, v26, v26
	v_fmac_f32_e32 v0, v28, v28
	v_fmac_f32_e32 v0, v29, v29
	s_nop 1
	v_mov_b32_dpp v26, v0 quad_perm:[1,0,3,2] row_mask:0xf bank_mask:0xf
	s_waitcnt lgkmcnt(0)
	v_add_f32_e32 v0, v0, v26
	s_nop 1
	v_mov_b32_dpp v26, v0 quad_perm:[2,3,0,1] row_mask:0xf bank_mask:0xf
	s_waitcnt lgkmcnt(0)
	v_add_f32_e32 v0, v0, v26
	s_nop 1
	v_mov_b32_dpp v26, v0 row_half_mirror row_mask:0xf bank_mask:0xf
	s_waitcnt lgkmcnt(0)
	v_add_f32_e32 v0, v0, v26
	s_nop 1
	v_mov_b32_dpp v26, v0 row_mirror row_mask:0xf bank_mask:0xf
	s_and_saveexec_b64 s[2:3], s[38:39]
	s_cbranch_execz .LBB0_1160
	s_waitcnt lgkmcnt(0)
	v_add_f32_e32 v0, v0, v26
	global_atomic_add_f32 v[126:127], v0, off offset:144

.LBB0_1164:
	v_mul_f32_e32 v0, v23, v23
	v_fmac_f32_e32 v0, v22, v22
	v_fmac_f32_e32 v0, v24, v24
	v_fmac_f32_e32 v0, v25, v25
	s_nop 1
	v_mov_b32_dpp v22, v0 quad_perm:[1,0,3,2] row_mask:0xf bank_mask:0xf
	s_waitcnt lgkmcnt(0)
	v_add_f32_e32 v0, v0, v22
	s_nop 1
	v_mov_b32_dpp v22, v0 quad_perm:[2,3,0,1] row_mask:0xf bank_mask:0xf
	s_waitcnt lgkmcnt(0)
	v_add_f32_e32 v0, v0, v22
	s_nop 1
	v_mov_b32_dpp v22, v0 row_half_mirror row_mask:0xf bank_mask:0xf
	s_waitcnt lgkmcnt(0)
	v_add_f32_e32 v0, v0, v22
	s_nop 1
	v_mov_b32_dpp v22, v0 row_mirror row_mask:0xf bank_mask:0xf
	s_and_saveexec_b64 s[2:3], s[38:39]
	s_cbranch_execz .LBB0_1166
	s_waitcnt lgkmcnt(0)
	v_add_f32_e32 v0, v0, v22
	global_atomic_add_f32 v[126:127], v0, off offset:160

.LBB0_1170:
	v_mul_f32_e32 v0, v19, v19
	v_fmac_f32_e32 v0, v18, v18
	v_fmac_f32_e32 v0, v20, v20
	v_fmac_f32_e32 v0, v21, v21
	s_nop 1
	v_mov_b32_dpp v18, v0 quad_perm:[1,0,3,2] row_mask:0xf bank_mask:0xf
	s_waitcnt lgkmcnt(0)
	v_add_f32_e32 v0, v0, v18
	s_nop 1
	v_mov_b32_dpp v18, v0 quad_perm:[2,3,0,1] row_mask:0xf bank_mask:0xf
	s_waitcnt lgkmcnt(0)
	v_add_f32_e32 v0, v0, v18
	s_nop 1
	v_mov_b32_dpp v18, v0 row_half_mirror row_mask:0xf bank_mask:0xf
	s_waitcnt lgkmcnt(0)
	v_add_f32_e32 v0, v0, v18
	s_nop 1
	v_mov_b32_dpp v18, v0 row_mirror row_mask:0xf bank_mask:0xf
	s_and_saveexec_b64 s[2:3], s[38:39]
	s_cbranch_execz .LBB0_1172
	s_waitcnt lgkmcnt(0)
	v_add_f32_e32 v0, v0, v18
	global_atomic_add_f32 v[126:127], v0, off offset:176

.LBB0_1176:
	v_mul_f32_e32 v0, v15, v15
	v_fmac_f32_e32 v0, v14, v14
	v_fmac_f32_e32 v0, v16, v16
	v_fmac_f32_e32 v0, v17, v17
	s_nop 1
	v_mov_b32_dpp v14, v0 quad_perm:[1,0,3,2] row_mask:0xf bank_mask:0xf
	s_waitcnt lgkmcnt(0)
	v_add_f32_e32 v0, v0, v14
	s_nop 1
	v_mov_b32_dpp v14, v0 quad_perm:[2,3,0,1] row_mask:0xf bank_mask:0xf
	s_waitcnt lgkmcnt(0)
	v_add_f32_e32 v0, v0, v14
	s_nop 1
	v_mov_b32_dpp v14, v0 row_half_mirror row_mask:0xf bank_mask:0xf
	s_waitcnt lgkmcnt(0)
	v_add_f32_e32 v0, v0, v14
	s_nop 1
	v_mov_b32_dpp v14, v0 row_mirror row_mask:0xf bank_mask:0xf
	s_and_saveexec_b64 s[2:3], s[38:39]
	s_cbranch_execz .LBB0_1178
	s_waitcnt lgkmcnt(0)
	v_add_f32_e32 v0, v0, v14
	global_atomic_add_f32 v[126:127], v0, off offset:192

.LBB0_1182:
	v_mul_f32_e32 v0, v11, v11
	v_fmac_f32_e32 v0, v10, v10
	v_fmac_f32_e32 v0, v12, v12
	v_fmac_f32_e32 v0, v13, v13
	s_nop 1
	v_mov_b32_dpp v10, v0 quad_perm:[1,0,3,2] row_mask:0xf bank_mask:0xf
	s_waitcnt lgkmcnt(0)
	v_add_f32_e32 v0, v0, v10
	s_nop 1
	v_mov_b32_dpp v10, v0 quad_perm:[2,3,0,1] row_mask:0xf bank_mask:0xf
	s_waitcnt lgkmcnt(0)
	v_add_f32_e32 v0, v0, v10
	s_nop 1
	v_mov_b32_dpp v10, v0 row_half_mirror row_mask:0xf bank_mask:0xf
	s_waitcnt lgkmcnt(0)
	v_add_f32_e32 v0, v0, v10
	s_nop 1
	v_mov_b32_dpp v10, v0 row_mirror row_mask:0xf bank_mask:0xf
	s_and_saveexec_b64 s[2:3], s[38:39]
	s_cbranch_execz .LBB0_1184
	s_waitcnt lgkmcnt(0)
	v_add_f32_e32 v0, v0, v10
	global_atomic_add_f32 v[126:127], v0, off offset:208

.LBB0_1188:
	v_mul_f32_e32 v0, v7, v7
	v_fmac_f32_e32 v0, v6, v6
	v_fmac_f32_e32 v0, v8, v8
	v_fmac_f32_e32 v0, v9, v9
	s_nop 1
	v_mov_b32_dpp v6, v0 quad_perm:[1,0,3,2] row_mask:0xf bank_mask:0xf
	s_waitcnt lgkmcnt(0)
	v_add_f32_e32 v0, v0, v6
	s_nop 1
	v_mov_b32_dpp v6, v0 quad_perm:[2,3,0,1] row_mask:0xf bank_mask:0xf
	s_waitcnt lgkmcnt(0)
	v_add_f32_e32 v0, v0, v6
	s_nop 1
	v_mov_b32_dpp v6, v0 row_half_mirror row_mask:0xf bank_mask:0xf
	s_waitcnt lgkmcnt(0)
	v_add_f32_e32 v0, v0, v6
	s_nop 1
	v_mov_b32_dpp v6, v0 row_mirror row_mask:0xf bank_mask:0xf
	s_and_saveexec_b64 s[2:3], s[38:39]
	s_cbranch_execz .LBB0_1190
	s_waitcnt lgkmcnt(0)
	v_add_f32_e32 v0, v0, v6
	global_atomic_add_f32 v[126:127], v0, off offset:224

.LBB0_1194:
	v_mul_f32_e32 v0, v3, v3
	v_fmac_f32_e32 v0, v2, v2
	v_fmac_f32_e32 v0, v4, v4
	v_fmac_f32_e32 v0, v5, v5
	s_nop 1
	v_mov_b32_dpp v2, v0 quad_perm:[1,0,3,2] row_mask:0xf bank_mask:0xf
	s_waitcnt lgkmcnt(0)
	v_add_f32_e32 v0, v0, v2
	s_nop 1
	v_mov_b32_dpp v2, v0 quad_perm:[2,3,0,1] row_mask:0xf bank_mask:0xf
	s_waitcnt lgkmcnt(0)
	v_add_f32_e32 v0, v0, v2
	s_nop 1
	v_mov_b32_dpp v2, v0 row_half_mirror row_mask:0xf bank_mask:0xf
	s_waitcnt lgkmcnt(0)
	v_add_f32_e32 v0, v0, v2
	s_nop 1
	v_mov_b32_dpp v2, v0 row_mirror row_mask:0xf bank_mask:0xf
	s_and_saveexec_b64 s[2:3], s[38:39]
	s_cbranch_execz .LBB0_997
	s_waitcnt lgkmcnt(0)
	v_add_f32_e32 v0, v0, v2
	global_atomic_add_f32 v[126:127], v0, off offset:240
	s_branch .LBB0_997
